# v35 + static s_setprio 1 for the map-1 (younger) waves during the prompt tile loop
# speedup vs baseline: 1.0028x; 1.0028x over previous
; #define GASP __attribute__((address_space(1)))
;     ...
;     const int S = SAMPLE ? PAST + DECS : SEQ, qpos0 = SAMPLE ? PAST : qi * 128 + sub * 32, rowq0 = SAMPLE ? NP + b * 32 : b * SEQ + qi * 128 + sub * 32;
;     const int NT = SAMPLE ? (PAST + DECS + 63) / 64 : 2 * qi + 2;
;     const int ntw = SAMPLE ? NT : min(NT, (qpos0 >> 6) + 1);
;     const float slope2 = exp2f(-2.f * (float)(h + 1)) * LOG2E;
;     bf16x8 qf[4];
;     { const bf16_t* qp = QB + (size_t)(rowq0 + r) * 512 + h * 128 + map * 64 + hi * 8;
; #pragma unroll
;       for (int d0 = 0; d0 < 4; ++d0) qf[d0] = *(const GASP bf16x8*)(qp + d0 * 16); }
;     f32x16 OT[NEB];
; #pragma unroll
;     for (int e = 0; e < NEB; ++e)
; #pragma unroll
;         for (int i = 0; i < 16; ++i) OT[e][i] = 0.f;
;     float m = -1e30f, l = 0.f;
;     const int lkey = tid >> 3, lc = tid & 7;
;     u32x4 pfA[NPF], pfB[SAMPLE ? 1 : NPF];
;     const float* ck = p.in[2]; const float* cv = p.in[3];
;     ...
;     const int i16 = lane & 15;
;     const int vlane_off = (4 * hi + (i16 >> 2)) * DA_VRS + (16 * ((lane >> 4) & 1) + 4 * (i16 & 3)) * 2;
;     const int tq = qpos0 + r;
;     ...
;     DA_ISSUE(pfA, 0); DA_WRITE(pfA, 0, 0);
;     if constexpr (SAMPLE) {
;         asm volatile("" : "+v"(qf[0]), "+v"(qf[1]), "+v"(qf[2]), "+v"(qf[3]));
;         __syncthreads();
; #pragma unroll 1
;         for (int tt = 0; tt < NT; ++tt) {
;             if (tt + 1 < NT) DA_ISSUE(pfA, tt + 1);
;             DA_COMPUTE(tt, tt & 1);
;             if (tt + 1 < NT) DA_WRITE(pfA, tt + 1, (tt + 1) & 1);
;             __syncthreads();
;         }
;     } else {
;     if (NT > 1) DA_ISSUE(pfA, 1);
;     asm volatile("" : "+v"(qf[0]), "+v"(qf[1]), "+v"(qf[2]), "+v"(qf[3]));
;     __syncthreads();
.LBB0_923:
	s_add_i32 s5, s4, 0xffffff80
	s_waitcnt vmcnt(11)
	v_mov_b32_e32 v24, v208
	s_lshr_b32 s6, s5, 6
	s_sub_i32 s7, 15, s6
	v_readfirstlane_b32 s8, v24
	s_bfe_u32 s10, s8, 0x20006
	s_lshl_b32 s5, s7, 7
	s_lshl_b32 s15, s10, 5
	s_or_b32 s28, s15, s5
	s_lshl_b32 s5, s4, 9
	v_and_b32_e32 v149, 31, v24
	s_and_b32 s11, s5, 0x7800
	s_and_b32 s14, s4, 3
	v_or_b32_e32 v0, s11, v149
	v_ashrrev_i32_e32 v25, 3, v24
	v_or_b32_e32 v146, s28, v0
	s_lshl_b32 s5, s14, 7
	s_waitcnt vmcnt(10)
	v_and_b32_e32 v26, 7, v24
	s_waitcnt vmcnt(4)
	v_add_u32_e32 v20, s11, v25
	s_ashr_i32 s9, s8, 8
	v_lshlrev_b32_e32 v0, 10, v146
	v_ashrrev_i32_e32 v21, 31, v20
	v_lshl_or_b32 v148, v26, 4, s5
	v_lshl_add_u64 v[2:3], s[70:71], 0, v[0:1]
	s_lshl_b32 s30, s14, 8
	s_lshl_b32 s12, s9, 6
	v_lshlrev_b64 v[10:11], 10, v[20:21]
	v_lshlrev_b32_e32 v21, 1, v148
	v_bfe_u32 v152, v24, 5, 1
	v_lshl_add_u64 v[2:3], v[2:3], 0, s[30:31]
	s_ashr_i32 s13, s12, 31
	v_or_b32_e32 v10, v10, v21
	v_lshl_add_u64 v[2:3], s[12:13], 1, v[2:3]
	v_lshlrev_b32_e32 v0, 4, v152
	v_lshl_add_u64 v[6:7], s[72:73], 0, v[10:11]
	v_lshl_add_u64 v[18:19], v[2:3], 0, v[0:1]
	global_load_dwordx4 v[2:5], v[6:7], off offset:16
	s_nop 0
	global_load_dwordx4 v[6:9], v[6:7], off
	s_waitcnt vmcnt(2)
	v_lshl_add_u64 v[14:15], s[74:75], 0, v[10:11]
	global_load_dwordx4 v[10:13], v[14:15], off offset:16
	s_nop 0
	global_load_dwordx4 v[14:17], v[14:15], off
	s_nop 0
	global_load_dwordx4 v[98:101], v[18:19], off offset:96
	global_load_dwordx4 v[102:105], v[18:19], off offset:64
	global_load_dwordx4 v[106:109], v[18:19], off offset:32
	global_load_dwordx4 v[110:113], v[18:19], off
	v_add_u32_e32 v18, 64, v20
	v_ashrrev_i32_e32 v19, 31, v18
	v_lshlrev_b64 v[18:19], 10, v[18:19]
	v_or_b32_e32 v18, v18, v21
	v_lshl_add_u64 v[22:23], s[74:75], 0, v[18:19]
	v_lshl_add_u64 v[18:19], s[72:73], 0, v[18:19]
	global_load_dwordx4 v[122:125], v[22:23], off offset:16
	global_load_dwordx4 v[126:129], v[22:23], off
	global_load_dwordx4 v[114:117], v[18:19], off offset:16
	global_load_dwordx4 v[118:121], v[18:19], off
	s_not_b32 s12, s14
	s_lshl_b32 s13, s12, 1
	v_and_b32_e32 v19, 16, v24
	v_lshlrev_b32_e32 v21, 2, v24
	v_bfe_u32 v22, v24, 2, 1
	s_lshl_b32 s12, s7, 1
	s_lshr_b32 s7, s28, 6
	v_lshrrev_b32_e32 v18, 2, v24
	v_lshlrev_b32_e32 v23, 5, v24
	v_ldexp_f32 v24, 1.0, s13
	v_and_or_b32 v19, v21, 12, v19
	v_mul_u32_u24_e32 v21, 0x2400, v22
	v_mul_lo_u32 v22, v25, s90
	s_add_i32 s13, s12, 2
	s_add_i32 s7, s7, 1
	v_lshlrev_b32_e32 v147, 2, v152
	v_and_b32_e32 v23, 0x60, v23
	v_mul_lo_u32 v25, v25, s88
	v_add3_u32 v21, 0, v21, v22
	s_min_u32 s14, s13, s7
	s_mul_i32 s7, s9, 0x2400
	v_lshlrev_b32_e32 v26, 5, v26
	v_and_or_b32 v18, v18, 3, v147
	v_add_u32_e32 v22, 0, v25
	v_add_u32_e32 v154, v21, v23
	s_add_i32 s7, s7, 0
	v_mul_u32_u24_e32 v18, 0x140, v18
	v_add_u32_e32 v155, v22, v26
	v_lshl_or_b32 v18, v19, 1, v18
	s_lshl_b32 s6, s6, 7
	v_mul_f32_e32 v153, 0x3fb8aa3b, v24
	v_add_u32_e32 v156, 0, v18
	v_add_u32_e32 v150, 0xc0, v20
	s_mov_b32 s11, 3
	v_add_u32_e32 v157, 0xe000, v156
	v_mov_b32_e32 v163, 0xf149f2ca
	v_mov_b32_e32 v159, 0
	s_waitcnt vmcnt(10)
	ds_write_b128 v154, v[6:9]
	ds_write_b128 v154, v[2:5] offset:16
	s_waitcnt vmcnt(8)
	ds_write_b128 v155, v[14:17] offset:18432
	ds_write_b128 v155, v[10:13] offset:18448
	v_mov_b32_e32 v2, s7
	v_mad_u32_u24 v19, v149, s90, v2
	v_or_b32_e32 v2, s15, v149
	v_or_b32_e32 v2, 0x780, v2
	v_sub_u32_e32 v2, v2, v147
	v_mov_b32_e32 v16, v1
	v_mov_b32_e32 v17, v1
	v_subrev_u32_e32 v158, s6, v2
	v_mov_b32_e32 v2, v1
	v_mov_b32_e32 v3, v1
	v_mov_b32_e32 v4, v1
	v_mov_b32_e32 v5, v1
	v_mov_b32_e32 v6, v1
	v_mov_b32_e32 v7, v1
	v_mov_b32_e32 v8, v1
	v_mov_b32_e32 v9, v1
	v_mov_b32_e32 v10, v1
	v_mov_b32_e32 v11, v1
	v_mov_b32_e32 v12, v1
	v_mov_b32_e32 v13, v1
	v_mov_b32_e32 v14, v1
	v_mov_b32_e32 v15, v1
	v_add_u32_e32 v162, v19, v0
	v_mov_b64_e32 v[32:33], v[16:17]
	v_mov_b64_e32 v[48:49], v[16:17]
	v_mov_b64_e32 v[64:65], v[16:17]
	v_mov_b64_e32 v[30:31], v[14:15]
	v_mov_b64_e32 v[28:29], v[12:13]
	v_mov_b64_e32 v[26:27], v[10:11]
	v_mov_b64_e32 v[24:25], v[8:9]
	v_mov_b64_e32 v[22:23], v[6:7]
	v_mov_b64_e32 v[20:21], v[4:5]
	v_mov_b64_e32 v[18:19], v[2:3]
	v_mov_b64_e32 v[46:47], v[14:15]
	v_mov_b64_e32 v[44:45], v[12:13]
	v_mov_b64_e32 v[42:43], v[10:11]
	v_mov_b64_e32 v[40:41], v[8:9]
	v_mov_b64_e32 v[38:39], v[6:7]
	v_mov_b64_e32 v[36:37], v[4:5]
	v_mov_b64_e32 v[34:35], v[2:3]
	v_mov_b64_e32 v[62:63], v[14:15]
	v_mov_b64_e32 v[60:61], v[12:13]
	v_mov_b64_e32 v[58:59], v[10:11]
	v_mov_b64_e32 v[56:57], v[8:9]
	v_mov_b64_e32 v[54:55], v[6:7]
	v_mov_b64_e32 v[52:53], v[4:5]
	v_mov_b64_e32 v[50:51], v[2:3]
	v_mov_b32_e32 v210, 0
	v_mul_f32_e32 v211, 1.0, v153
	v_mul_f32_e32 v212, 2.0, v153
	v_mul_f32_e32 v213, 0x40400000, v153
	v_mul_f32_e32 v214, 0x41000000, v153
	v_mul_f32_e32 v215, 0x41100000, v153
	v_mul_f32_e32 v216, 0x41200000, v153
	v_mul_f32_e32 v217, 0x41300000, v153
	v_mul_f32_e32 v218, 0x41800000, v153
	v_mul_f32_e32 v219, 0x41880000, v153
	v_mul_f32_e32 v220, 0x41900000, v153
	v_mul_f32_e32 v221, 0x41980000, v153
	v_mul_f32_e32 v222, 0x41c00000, v153
	v_mul_f32_e32 v223, 0x41c80000, v153
	v_mul_f32_e32 v224, 0x41d00000, v153
	v_mul_f32_e32 v225, 0x41d80000, v153
	v_mul_f32_e32 v226, 0x42000000, v153
	v_mul_f32_e32 v227, 0x42040000, v153
	v_mul_f32_e32 v228, 0x42080000, v153
	v_mul_f32_e32 v229, 0x420c0000, v153
	v_mul_f32_e32 v230, 0x42200000, v153
	v_mul_f32_e32 v231, 0x42240000, v153
	v_mul_f32_e32 v232, 0x42280000, v153
	v_mul_f32_e32 v233, 0x422c0000, v153
	v_mul_f32_e32 v234, 0x42400000, v153
	v_mul_f32_e32 v235, 0x42440000, v153
	v_mul_f32_e32 v236, 0x42480000, v153
	v_mul_f32_e32 v237, 0x424c0000, v153
	v_mul_f32_e32 v238, 0x42600000, v153
	v_mul_f32_e32 v239, 0x42640000, v153
	v_mul_f32_e32 v240, 0x42680000, v153
	v_mul_f32_e32 v241, 0x426c0000, v153
	s_waitcnt vmcnt(4)
	s_waitcnt lgkmcnt(0)
	s_barrier
	s_cmp_lg_u32 s9, 1
	s_cbranch_scc1 .Lp_prio_skip
	s_setprio 1
.Lp_prio_skip:
	s_branch .LBB0_925
.LBB0_924:
	s_add_i32 s11, s11, 2
	v_add_u32_e32 v158, 0xffffff80, v158
	s_cmp_lt_u32 s15, s12
	v_add_u32_e32 v150, 0x80, v150
	s_waitcnt lgkmcnt(0)
	s_barrier
	s_cbranch_scc0 .LBB0_939

;     ...
;     l += __shfl_xor(l, 32);
;     if constexpr (SAMPLE) {
;         LAS float* SLB = (LAS float*)L; LAS f32x2* ML = (LAS f32x2*)(L + 131072); LAS float* SS = (LAS float*)(L + 131072 + 2048);
;         if (hi == 0) ML[(map * 4 + sub) * 32 + r] = (f32x2){m, l};
;         __syncthreads();
;         float M = -1e30f;
; #pragma unroll
;         for (int s4 = 0; s4 < 4; ++s4) M = fmaxf(M, ML[(map * 4 + s4) * 32 + r][0]);
;         float Lsum = 0.f;
; #pragma unroll
;         for (int s4 = 0; s4 < 4; ++s4) { const f32x2 v = ML[(map * 4 + s4) * 32 + r]; Lsum += v[1] * fexp2(v[0] - M); }
;         const float f = fexp2(m - M) * frcp(Lsum);
;         LAS float* mine = SLB + (map * 4 + sub) * 4096;
; #pragma unroll
;         for (int eb = 0; eb < 4; ++eb)
; #pragma unroll
;             for (int rg = 0; rg < 16; ++rg) mine[(eb * 32 + (rg & 3) + 8 * (rg >> 2) + 4 * hi) * 32 + r] = OT[eb][rg] * f;
;         __syncthreads();
;         float o16[16]; float ss = 0.f;
;         if (map == 0) {
; #pragma unroll
;             for (int rg = 0; rg < 16; ++rg) { const int idx = (sub * 32 + (rg & 3) + 8 * (rg >> 2) + 4 * hi) * 32 + r;
;                 const float o1 = (SLB[idx] + SLB[4096 + idx]) + (SLB[2 * 4096 + idx] + SLB[3 * 4096 + idx]);
;                 const float o2 = (SLB[4 * 4096 + idx] + SLB[5 * 4096 + idx]) + (SLB[6 * 4096 + idx] + SLB[7 * 4096 + idx]);
;                 const float o = o1 - lam * o2; o16[rg] = o; ss += o * o; }
;             ss += __shfl_xor(ss, 32);
;             if (hi == 0) SS[sub * 32 + r] = ss;
;         }
;         __syncthreads();
;         if (map == 0) {
;             ss = (SS[r] + SS[32 + r]) + (SS[64 + r] + SS[96 + r]);
;             const float rms = 0.8f / sqrtf(ss * (1.f / 128.f) + LN_EPS);
;             const float* sg = p.in[16];
;             bf16_t* op = (bf16_t*)(ws + O_MIX) + (size_t)(rowq0 + r) * D + h * 128 + sub * 32 + 4 * hi;
; #pragma unroll
;             for (int g4 = 0; g4 < 4; ++g4) { const f32x4 gv = *(const GASP f32x4*)(sg + sub * 32 + 8 * g4 + 4 * hi);
;                 u32x2 w; w.x = pk2(o16[4 * g4] * rms * gv[0], o16[4 * g4 + 1] * rms * gv[1]); w.y = pk2(o16[4 * g4 + 2] * rms * gv[2], o16[4 * g4 + 3] * rms * gv[3]);
;                 *(GASP u32x2*)(op + 8 * g4) = w; }
;         }
;         __syncthreads();
;     } else {
;         const float inv = frcp(l);
;         LAS float* X = (LAS float*)L + sub * 4096;
.LBB0_939:
	s_setprio 0
	ds_bpermute_b32 v0, v171, v159
	s_lshl_b32 s6, s10, 14
	s_add_i32 s6, s6, 0
	v_lshlrev_b32_e32 v66, 2, v149
	v_lshlrev_b32_e32 v67, 9, v152
	s_waitcnt lgkmcnt(0)
	v_add_f32_e32 v0, v159, v0
	v_rcp_f32_e32 v0, v0
	s_cmp_lg_u32 s9, 1
	v_add3_u32 v66, s6, v66, v67
	s_cbranch_scc1 .LBB0_941
	v_mul_f32_e32 v67, v50, v0
	v_mul_f32_e32 v68, v51, v0
	ds_write2_b32 v66, v67, v68 offset1:32
	v_mul_f32_e32 v67, v52, v0
	v_mul_f32_e32 v68, v53, v0
	ds_write2_b32 v66, v67, v68 offset0:64 offset1:96
	v_mul_f32_e32 v67, v54, v0
	v_mul_f32_e32 v68, v55, v0
	v_add_u32_e32 v69, 0x400, v66
	ds_write2_b32 v69, v67, v68 offset1:32
	v_mul_f32_e32 v67, v56, v0
	v_mul_f32_e32 v68, v57, v0
	ds_write2_b32 v69, v67, v68 offset0:64 offset1:96
	v_mul_f32_e32 v67, v58, v0
	v_mul_f32_e32 v68, v59, v0
	v_add_u32_e32 v69, 0x800, v66
	ds_write2_b32 v69, v67, v68 offset1:32
	v_mul_f32_e32 v67, v60, v0
	v_mul_f32_e32 v68, v61, v0
	ds_write2_b32 v69, v67, v68 offset0:64 offset1:96
	v_mul_f32_e32 v67, v62, v0
	v_mul_f32_e32 v68, v63, v0
	v_add_u32_e32 v69, 0xc00, v66
	ds_write2_b32 v69, v67, v68 offset1:32
	v_mul_f32_e32 v67, v64, v0
	v_mul_f32_e32 v68, v65, v0
	ds_write2_b32 v69, v67, v68 offset0:64 offset1:96
	v_mul_f32_e32 v67, v34, v0
	v_mul_f32_e32 v68, v35, v0
	v_add_u32_e32 v69, 0x1000, v66
	ds_write2_b32 v69, v67, v68 offset1:32
	v_mul_f32_e32 v67, v36, v0
	v_mul_f32_e32 v68, v37, v0
	ds_write2_b32 v69, v67, v68 offset0:64 offset1:96
	v_mul_f32_e32 v67, v38, v0
	v_mul_f32_e32 v68, v39, v0
	v_add_u32_e32 v69, 0x1400, v66
	ds_write2_b32 v69, v67, v68 offset1:32
	v_mul_f32_e32 v67, v40, v0
	v_mul_f32_e32 v68, v41, v0
	ds_write2_b32 v69, v67, v68 offset0:64 offset1:96
	v_mul_f32_e32 v67, v42, v0
	v_mul_f32_e32 v68, v43, v0
	v_add_u32_e32 v69, 0x1800, v66
	ds_write2_b32 v69, v67, v68 offset1:32
	v_mul_f32_e32 v67, v44, v0
	v_mul_f32_e32 v68, v45, v0
	ds_write2_b32 v69, v67, v68 offset0:64 offset1:96
	v_mul_f32_e32 v67, v46, v0
	v_mul_f32_e32 v68, v47, v0
	v_add_u32_e32 v69, 0x1c00, v66
	ds_write2_b32 v69, v67, v68 offset1:32
	v_mul_f32_e32 v67, v48, v0
	v_mul_f32_e32 v68, v49, v0
	ds_write2_b32 v69, v67, v68 offset0:64 offset1:96
	v_mul_f32_e32 v67, v18, v0
	v_mul_f32_e32 v68, v19, v0
	v_add_u32_e32 v69, 0x2000, v66
	ds_write2_b32 v69, v67, v68 offset1:32
	v_mul_f32_e32 v67, v20, v0
	v_mul_f32_e32 v68, v21, v0
	ds_write2_b32 v69, v67, v68 offset0:64 offset1:96
	v_mul_f32_e32 v67, v22, v0
	v_mul_f32_e32 v68, v23, v0
	v_add_u32_e32 v69, 0x2400, v66
	ds_write2_b32 v69, v67, v68 offset1:32
	v_mul_f32_e32 v67, v24, v0
	v_mul_f32_e32 v68, v25, v0
	ds_write2_b32 v69, v67, v68 offset0:64 offset1:96
	v_mul_f32_e32 v67, v26, v0
	v_mul_f32_e32 v68, v27, v0
	v_add_u32_e32 v69, 0x2800, v66
	ds_write2_b32 v69, v67, v68 offset1:32
	v_mul_f32_e32 v67, v28, v0
	v_mul_f32_e32 v68, v29, v0
	ds_write2_b32 v69, v67, v68 offset0:64 offset1:96
	v_mul_f32_e32 v67, v30, v0
	v_mul_f32_e32 v68, v31, v0
	v_add_u32_e32 v69, 0x2c00, v66
	ds_write2_b32 v69, v67, v68 offset1:32
	v_mul_f32_e32 v67, v32, v0
	v_mul_f32_e32 v68, v33, v0
	ds_write2_b32 v69, v67, v68 offset0:64 offset1:96
	v_mul_f32_e32 v67, v2, v0
	v_mul_f32_e32 v68, v3, v0
	v_add_u32_e32 v69, 0x3000, v66
	ds_write2_b32 v69, v67, v68 offset1:32
	v_mul_f32_e32 v67, v4, v0
	v_mul_f32_e32 v68, v5, v0
	ds_write2_b32 v69, v67, v68 offset0:64 offset1:96
	v_mul_f32_e32 v67, v6, v0
	v_mul_f32_e32 v68, v7, v0
	v_add_u32_e32 v69, 0x3400, v66
	ds_write2_b32 v69, v67, v68 offset1:32
	v_mul_f32_e32 v67, v8, v0
	v_mul_f32_e32 v68, v9, v0
	ds_write2_b32 v69, v67, v68 offset0:64 offset1:96
	v_mul_f32_e32 v67, v10, v0
	v_mul_f32_e32 v68, v11, v0
	v_add_u32_e32 v69, 0x3800, v66
	ds_write2_b32 v69, v67, v68 offset1:32
	v_mul_f32_e32 v67, v12, v0
	v_mul_f32_e32 v68, v13, v0
	ds_write2_b32 v69, v67, v68 offset0:64 offset1:96
	v_mul_f32_e32 v67, v14, v0
	v_mul_f32_e32 v68, v15, v0
	v_add_u32_e32 v69, 0x3c00, v66
	ds_write2_b32 v69, v67, v68 offset1:32
	v_mul_f32_e32 v67, v16, v0
	v_mul_f32_e32 v68, v17, v0
	ds_write2_b32 v69, v67, v68 offset0:64 offset1:96
